# in-proj rounds 1-3: adjacent ranks share the A panel (same row tile) instead of the weight panel
# speedup vs baseline: 1.0046x; 1.0046x over previous
;     __host__ __device__ bool next(int i, Unit& u) const {
;         const long L = (long)i * G + c; if (L >= nwg) return false;
;         int wgid = (int)L; { const int q = nwg / NXCD, r = nwg % NXCD, xcd = wgid % NXCD, off = wgid / NXCD; wgid = (xcd < r ? xcd * (q + 1) : r * (q + 1) + (xcd - r) * q) + off; }
;         const int nig = WGM * nN, gid = wgid / nig, fm = gid * WGM, gsz = (nM - fm) < WGM ? (nM - fm) : WGM;
;         u.pm = fm + ((wgid % nig) % gsz); u.pn = (wgid % nig) / gsz; return true;
;     }
.LBB0_173:
	s_ashr_i32 s30, s40, 3
	s_add_i32 s30, s42, s30
	s_ashr_i32 s31, s30, 31
	s_lshr_b32 s31, s31, 25
	s_add_i32 s31, s30, s31
	s_ashr_i32 s40, s31, 7
	s_lshl_b32 s40, s40, 3
	s_sub_i32 s41, 64, s40
	s_min_i32 s41, s41, 8
	s_abs_i32 s42, s41
	v_cvt_f32_u32_e32 v4, s42
	s_sub_i32 s44, 0, s42
	s_and_b32 s31, s31, 0xffffff80
	s_sub_i32 s31, s30, s31
	v_rcp_iflag_f32_e32 v4, v4
	s_abs_i32 s30, s31
	s_xor_b32 s43, s31, s41
	s_ashr_i32 s43, s43, 31
	v_mul_f32_e32 v4, 0x4f7ffffe, v4
	v_cvt_u32_f32_e32 v4, v4
	s_nop 0
	v_readfirstlane_b32 s45, v4
	s_mul_i32 s44, s44, s45
	s_mul_hi_u32 s44, s45, s44
	s_add_i32 s45, s45, s44
	s_mul_hi_u32 s44, s30, s45
	s_mul_i32 s45, s44, s42
	s_sub_i32 s30, s30, s45
	s_add_i32 s50, s44, 1
	s_sub_i32 s45, s30, s42
	s_cmp_ge_u32 s30, s42
	s_cselect_b32 s44, s50, s44
	s_cselect_b32 s30, s45, s30
	s_add_i32 s45, s44, 1
	s_cmp_ge_u32 s30, s42
	s_cselect_b32 s30, s45, s44
	s_xor_b32 s30, s30, s43
	s_sub_i32 s30, s30, s43
	s_mul_i32 s41, s30, s41
	s_sub_i32 s31, s31, s41
	s_add_i32 s40, s40, s31
	s_lshr_b32 s41, s66, 4
	s_and_b32 s41, s41, 7
	s_and_b32 s40, s40, -8
	s_or_b32 s40, s40, s41
	s_bfe_u32 s41, s66, 0x10003
	s_bfe_u32 s98, s66, 0x10007
	s_lshl_b32 s98, s98, 1
	s_or_b32 s41, s41, s98
	s_lshr_b32 s98, s30, 2
	s_add_i32 s41, s41, s98
	s_and_b32 s41, s41, 3
	s_and_b32 s30, s30, 12
	s_or_b32 s30, s30, s41
